# grid barrier: per-WG arrival flags polled by one master wave + release word (replaces two-level counters with returning atomics)
# speedup vs baseline: 1.0388x; 1.0011x over previous
; #define LAS __attribute__((address_space(3)))
; __global__ void __launch_bounds__(NTHR, 2) mk_fwd(Args a_by_value) {
;     extern __shared__ __attribute__((aligned(16))) unsigned char lds[];
;     LAS unsigned char* ldsl = (LAS unsigned char*)lds;
;     const int ph_lo = a_by_value.ph_lo, ph_hi = a_by_value.ph_hi;
;     const int wave_s = __builtin_amdgcn_readfirstlane((int)threadIdx.x >> 6);
;     ...
;         if (ph + 1 < ph_hi) cg::this_grid().sync();
_Z6mk_fwd4Args:
	s_load_dwordx2 s[24:25], s[0:1], 0xb8
	v_and_b32_e32 v1, 0x3ff, v0
	s_waitcnt lgkmcnt(0)
	s_cmp_ge_i32 s24, s25
	v_readfirstlane_b32 s3, v1
	s_cbranch_scc1 .LBB0_539
	s_lshr_b32 s3, s3, 6
	s_add_u32 s4, s0, 0xc0
	s_addc_u32 s5, s1, 0
	v_lshrrev_b32_e32 v2, 20, v0
	v_writelane_b32 v255, s4, 0
	v_lshrrev_b32_e32 v0, 10, v0
	v_or_b32_e32 v0, v0, v2
	v_writelane_b32 v255, s5, 1
	s_movk_i32 s4, 0x3ff
	v_and_or_b32 v0, v0, s4, v1
	s_add_i32 s4, 0, 0xb000
	v_writelane_b32 v255, s4, 2
	s_add_i32 s4, 0, 0x4800
	v_writelane_b32 v255, s4, 3
	v_cmp_eq_u32_e64 s[4:5], 0, v0
	v_mbcnt_lo_u32_b32 v2, -1, 0
	s_movk_i32 s31, 0x1600
	v_writelane_b32 v255, s4, 4
	s_mov_b32 s33, 0xffff0000
	s_movk_i32 s73, 0x100
	v_mov_b32_e32 v184, 0x358637bd
	s_mov_b32 s74, 0x800000
	s_mov_b32 s75, 0x20000
	v_mov_b32_e32 v1, 0
	s_movk_i32 s77, 0x400
	s_mov_b32 s78, 0x10000
	s_movk_i32 s80, 0x90
	s_movk_i32 s82, 0x1800
	s_movk_i32 s83, 0x110
	s_mov_b32 s87, 0xc2fc0000
	v_mov_b32_e32 v185, 0x201000
	s_movk_i32 s91, 0x7fff
	s_movk_i32 s92, 0xff
	s_add_i32 s93, 0, 0xdb34
	s_mov_b32 s94, 0x41000000
	s_movk_i32 s98, 0x6400
	v_mov_b32_e32 v186, 1
	v_mov_b64_e32 v[146:147], 0xaff
	v_mov_b64_e32 v[148:149], 0x200
	v_mov_b64_e32 v[150:151], 0x1ff
	v_mbcnt_hi_u32_b32 v187, -1, v2
	v_mov_b32_e32 v188, 0x3e000000
	v_mov_b32_e32 v189, 0x42800000
	v_mov_b32_e32 v190, 0x42000000
	v_not_b32_e32 v191, 63
	v_mov_b32_e32 v254, 0x7f800000
	v_mov_b32_e32 v196, 0xc00
	v_mov_b64_e32 v[152:153], 0xc80
	v_mov_b64_e32 v[154:155], 0xc7f
	v_mov_b32_e32 v194, 0x3e38aa3b
	v_mov_b32_e32 v195, 0x1c0
	s_movk_i32 s99, 0x7000
	s_mov_b32 s29, 0
	v_writelane_b32 v255, s5, 5
	s_mov_b64 s[34:35], 0x80
	s_mov_b64 s[38:39], 0x1000
	s_mov_b64 s[40:41], 0x10000
	s_mov_b32 s20, 0x3f803f80
	s_mov_b32 s100, 0
	s_mov_b32 s101, 0
	s_or_b32 s4, s2, s3
	s_cmp_lg_u32 s4, 0
	s_cbranch_scc1 .Lfb_noinit
	s_load_dwordx2 s[4:5], s[0:1], 0xb0
	v_lshlrev_b32_e32 v252, 4, v187
	v_add_u32_e32 v252, 0x4000, v252
	v_mov_b32_e32 v248, 0
	v_mov_b32_e32 v249, 0
	v_mov_b32_e32 v250, 0
	v_mov_b32_e32 v251, 0
	s_waitcnt lgkmcnt(0)
	global_store_dwordx4 v252, v[248:251], s[4:5]
	global_store_dwordx4 v252, v[248:251], s[4:5] offset:1024

; __global__ void __launch_bounds__(NTHR, 2) mk_fwd(Args a_by_value) {
;     ...
;         if (ph + 1 < ph_hi) cg::this_grid().sync();
.Lfb_fast:
	buffer_wbl2 sc1
	s_load_dwordx2 s[6:7], s[0:1], 0xb0
	s_add_u32 s100, s100, 1
	v_mov_b32_e32 v2, 1
	s_lshl_b32 s9, s2, 2
	s_add_u32 s9, s9, 0x4000
	v_mov_b32_e32 v0, s9
	s_waitcnt vmcnt(0) lgkmcnt(0)
	global_atomic_add v0, v2, s[6:7]
	s_cmp_lg_u32 s2, 0
	s_cbranch_scc1 .Lfb_member
	s_mov_b64 s[10:11], exec
	s_mov_b64 exec, -1
	v_lshlrev_b32_e32 v0, 4, v187
	v_add_u32_e32 v0, 0x4000, v0
	s_mov_b32 s13, 0x4000
.Lfb_spin_all:
	global_load_dwordx4 v[4:7], v0, s[6:7] sc1
	s_waitcnt vmcnt(0)
	v_min_u32_e32 v4, v4, v5
	v_min3_u32 v4, v4, v6, v7
	v_cmp_le_u32_e32 vcc, s100, v4
	s_nop 3
	s_cmp_eq_u64 vcc, -1
	s_cbranch_scc1 .Lfb_all_in
	s_sleep 1
	s_sub_u32 s13, s13, 1
	s_cmp_lg_u32 s13, 0
	s_cbranch_scc1 .Lfb_spin_all
.Lfb_all_in:
	s_mov_b64 exec, s[10:11]
	v_mov_b32_e32 v0, 0x4400
	s_nop 0
	global_atomic_add v0, v2, s[6:7]
	s_branch .Lfb_acquire
.Lfb_member:
	v_mov_b32_e32 v0, 0x4400
	s_mov_b32 s13, 0x4000
.Lfb_spin_rel:
	global_load_dword v3, v0, s[6:7] sc1
	s_waitcnt vmcnt(0)
	v_readfirstlane_b32 s12, v3
	s_nop 3
	s_cmp_ge_u32 s12, s100
	s_cbranch_scc1 .Lfb_acquire
	s_sleep 1
	s_sub_u32 s13, s13, 1
	s_cmp_lg_u32 s13, 0
	s_cbranch_scc1 .Lfb_spin_rel
